# L0 out-proj GEMM phase: WGs on XCDs 4-7 start 8us late so the HBM-bound f32 residual epilogues of the two chip halves do not coincide
# baseline (speedup 1.0000x reference)
;     __device__ __forceinline__ bool next(int i, Unit& u) const { if (!S.next(i, u)) return false; if (u.pn >= 4) u.pn += 2; return true; }
;     __host__ __device__ __forceinline__ bool next(int i, Unit& u) const {
;         const long L = (long)i * G + c; if (L >= nwg) return false;
;         int wgid = (int)L; { const int q = nwg / NXCD, r = nwg % NXCD, xcd = wgid % NXCD, off = wgid / NXCD; wgid = (xcd < r ? xcd * (q + 1) : r * (q + 1) + (xcd - r) * q) + off; }
;         const int nig = WGM * nN, gid = wgid / nig, fm = gid * WGM, gsz = (nM - fm) < WGM ? (nM - fm) : WGM;
;         u.pm = fm + ((wgid % nig) % gsz); u.pn = (wgid % nig) / gsz; return true;
; template <class Epi, class Sched, bool ALIGN_EPI = false, bool SP2 = false>
; __device__ __forceinline__ void gemm_phase(PG8_LAS unsigned char* lds, const Gemm g, const Sched& S, const Epi& E) {
;     ...
;     Unit cur, nxt; int ui = 0;
;     if (!S.next(0, cur)) return;
.LBB0_594:
	s_or_b64 exec, exec, s[6:7]
	v_readlane_b32 s0, v253, 0
	s_waitcnt lgkmcnt(0)
	v_mov_b32_e32 v1, v0
	v_mov_b32_e32 v2, v0
	s_cmpk_lt_i32 s0, 0x200
	s_barrier
	s_cselect_b64 s[36:37], -1, 0
	v_readlane_b32 s98, v253, 0
	s_nop 3
	s_and_b32 s98, s98, 4
	s_cmp_eq_u32 s98, 0
	s_cbranch_scc1 .Ldly_skip_p6
	s_memrealtime s[98:99]
	s_waitcnt lgkmcnt(0)
.Ldly_loop_p6:
	s_sleep 2
	s_memrealtime s[100:101]
	s_waitcnt lgkmcnt(0)
	s_sub_u32 s100, s100, s98
	s_cmp_lt_u32 s100, 800
	s_cbranch_scc1 .Ldly_loop_p6
.Ldly_skip_p6:
	s_cmpk_gt_i32 s0, 0x1ff
	v_readfirstlane_b32 s0, v2
	v_readlane_b32 s1, v253, 1
	s_cbranch_scc1 .LBB0_618
	v_readlane_b32 s2, v253, 0
	v_readlane_b32 s3, v253, 1
	s_ashr_i32 s3, s2, 31
	s_lshr_b32 s1, s3, 29
	s_add_i32 s1, s2, s1
	s_mov_b32 s4, s2
	s_and_b32 s2, s1, -8
	s_sub_i32 s2, s4, s2
	s_cmp_gt_i32 s2, -1
	s_cbranch_scc0 .LBB0_597
	s_lshl_b32 s4, s2, 6
	s_cbranch_execz .LBB0_598
	s_branch .LBB0_599

; __global__ void __launch_bounds__(NWAVES * 64, 2) fwd_mega(Args args) {
	.amdhsa_kernel _Z8fwd_mega4Args
		.amdhsa_group_segment_fixed_size 0
		.amdhsa_private_segment_fixed_size 0
		.amdhsa_kernarg_size 616
		.amdhsa_user_sgpr_count 2
		.amdhsa_user_sgpr_dispatch_ptr 0
		.amdhsa_user_sgpr_queue_ptr 0
		.amdhsa_user_sgpr_kernarg_segment_ptr 1
		.amdhsa_user_sgpr_dispatch_id 0
		.amdhsa_user_sgpr_kernarg_preload_length 0
		.amdhsa_user_sgpr_kernarg_preload_offset 0
		.amdhsa_user_sgpr_private_segment_size 0
		.amdhsa_uses_dynamic_stack 0
		.amdhsa_enable_private_segment 0
		.amdhsa_system_sgpr_workgroup_id_x 1
		.amdhsa_system_sgpr_workgroup_id_y 0
		.amdhsa_system_sgpr_workgroup_id_z 0
		.amdhsa_system_sgpr_workgroup_info 0
		.amdhsa_system_vgpr_workitem_id 0
		.amdhsa_next_free_vgpr 254
		.amdhsa_next_free_sgpr 102
		.amdhsa_accum_offset 256
		.amdhsa_reserve_vcc 1
		.amdhsa_float_round_mode_32 0
		.amdhsa_float_round_mode_16_64 0
		.amdhsa_float_denorm_mode_32 3
		.amdhsa_float_denorm_mode_16_64 3
		.amdhsa_dx10_clamp 1
		.amdhsa_ieee_mode 1
		.amdhsa_fp16_overflow 0
		.amdhsa_tg_split 0
		.amdhsa_exception_fp_ieee_invalid_op 0
		.amdhsa_exception_fp_denorm_src 0
		.amdhsa_exception_fp_ieee_div_zero 0
		.amdhsa_exception_fp_ieee_overflow 0
		.amdhsa_exception_fp_ieee_underflow 0
		.amdhsa_exception_fp_ieee_inexact 0
		.amdhsa_exception_int_div_zero 0
	.end_amdhsa_kernel

; __global__ void __launch_bounds__(NWAVES * 64, 2) fwd_mega(Args args) {
amdhsa.kernels:
  - .agpr_count:     0
    .args:
      - .offset:         0
        .size:           360
        .value_kind:     by_value
      - .offset:         360
        .size:           4
        .value_kind:     hidden_block_count_x
      - .offset:         364
        .size:           4
        .value_kind:     hidden_block_count_y
      - .offset:         368
        .size:           4
        .value_kind:     hidden_block_count_z
      - .offset:         372
        .size:           2
        .value_kind:     hidden_group_size_x
      - .offset:         374
        .size:           2
        .value_kind:     hidden_group_size_y
      - .offset:         376
        .size:           2
        .value_kind:     hidden_group_size_z
      - .offset:         378
        .size:           2
        .value_kind:     hidden_remainder_x
      - .offset:         380
        .size:           2
        .value_kind:     hidden_remainder_y
      - .offset:         382
        .size:           2
        .value_kind:     hidden_remainder_z
      - .offset:         400
        .size:           8
        .value_kind:     hidden_global_offset_x
      - .offset:         408
        .size:           8
        .value_kind:     hidden_global_offset_y
      - .offset:         416
        .size:           8
        .value_kind:     hidden_global_offset_z
      - .offset:         424
        .size:           2
        .value_kind:     hidden_grid_dims
      - .offset:         480
        .size:           4
        .value_kind:     hidden_dynamic_lds_size
    .group_segment_fixed_size: 0
    .kernarg_segment_align: 8
    .kernarg_segment_size: 616
    .language:       OpenCL C
    .language_version:
      - 2
      - 0
    .max_flat_workgroup_size: 512
    .name:           _Z8fwd_mega4Args
    .private_segment_fixed_size: 0
    .sgpr_count:     108
    .sgpr_spill_count: 111
    .symbol:         _Z8fwd_mega4Args.kd
    .uniform_work_group_size: 1
    .uses_dynamic_stack: false
    .vgpr_count:     254
    .vgpr_spill_count: 0
    .wavefront_size: 64
